# norm phase: shift/scale vector loads of quarters 1-3 issued with quarter 0's (no per-quarter drain), copies at the original positions
# baseline (speedup 1.0000x reference)
.LBB0_149:
	s_or_b64 exec, exec, s[0:1]
	v_min_i32_e32 v56, 0x10000, v54
	v_ashrrev_i32_e32 v56, 13, v56
	v_mul_i32_i24_e32 v56, 0x1800, v56
	v_ashrrev_i32_e32 v57, 31, v56
	v_lshl_add_u64 v[56:57], v[56:57], 2, s[24:25]
	v_lshl_add_u64 v[78:79], v[56:57], 0, v[48:49]
	v_add_co_u32_e64 v56, s[0:1], s10, v78
	s_waitcnt vmcnt(3)
	v_pk_mul_f32 v[80:81], v[44:45], v[44:45]
	v_addc_co_u32_e64 v57, s[0:1], 0, v79, s[0:1]
	global_load_dwordx4 v[70:73], v[56:57], off
	global_load_dwordx4 v[74:77], v[78:79], off
	v_lshl_add_u64 v[100:101], v[78:79], 0, s[6:7]
	global_load_dwordx4 v[104:107], v[100:101], off offset:1024
	global_load_dwordx4 v[108:111], v[78:79], off offset:1024
	global_load_dwordx4 v[112:115], v[100:101], off offset:2048
	global_load_dwordx4 v[116:119], v[78:79], off offset:2048
	global_load_dwordx4 v[120:123], v[100:101], off offset:3072
	global_load_dwordx4 v[124:127], v[78:79], off offset:3072
	v_pk_mul_f32 v[56:57], v[46:47], v[46:47]
	s_waitcnt vmcnt(10)
	v_pk_mul_f32 v[82:83], v[42:43], v[42:43]
	v_pk_mul_f32 v[84:85], v[40:41], v[40:41]
	v_pk_mov_b32 v[90:91], v[80:81], v[56:57] op_sel:[1,0]
	v_mov_b32_e32 v81, v57
	v_pk_mov_b32 v[56:57], v[84:85], v[82:83] op_sel:[1,0]
	v_mov_b32_e32 v85, v83
	s_waitcnt vmcnt(8)
	v_mul_f32_e32 v89, v33, v33
	v_mul_f32_e32 v86, v37, v37
	v_mul_f32_e32 v88, v39, v39
	v_pk_add_f32 v[80:81], v[90:91], v[80:81]
	v_pk_add_f32 v[56:57], v[56:57], v[84:85]
	v_mul_f32_e32 v69, v32, v32
	v_mul_f32_e32 v92, v34, v34
	v_mul_f32_e32 v93, v35, v35
	v_pk_fma_f32 v[82:83], v[36:37], v[36:37], v[86:87] op_sel_hi:[1,1,0]
	v_pk_fma_f32 v[86:87], v[38:39], v[38:39], v[88:89] op_sel_hi:[1,1,0]
	v_pk_add_f32 v[80:81], v[80:81], v[80:81] op_sel:[0,1] op_sel_hi:[1,0]
	v_pk_add_f32 v[56:57], v[56:57], v[56:57] op_sel:[0,1] op_sel_hi:[1,0]
	v_mov_b32_e32 v83, v92
	v_mov_b32_e32 v87, v93
	v_mov_b32_e32 v81, v69
	v_mov_b32_e32 v57, v89
	v_pk_add_f32 v[82:83], v[82:83], v[86:87]
	v_pk_add_f32 v[56:57], v[80:81], v[56:57]
	v_lshlrev_b64 v[54:55], 11, v[54:55]
	v_pk_add_f32 v[56:57], v[56:57], v[82:83]
	v_lshl_add_u64 v[82:83], v[50:51], 0, v[54:55]
	v_add_f32_e32 v56, v56, v57
	s_nop 1
	v_add_f32_dpp v56, v56, v56 quad_perm:[1,0,3,2] row_mask:0xf bank_mask:0xf bound_ctrl:1
	s_nop 1
	v_add_f32_dpp v56, v56, v56 quad_perm:[2,3,0,1] row_mask:0xf bank_mask:0xf bound_ctrl:1
	s_nop 1
	v_add_f32_dpp v56, v56, v56 row_half_mirror row_mask:0xf bank_mask:0xf bound_ctrl:1
	s_nop 1
	v_add_f32_dpp v56, v56, v56 row_mirror row_mask:0xf bank_mask:0xf bound_ctrl:1
	s_nop 1
	v_readlane_b32 s98, v56, 0
	v_readlane_b32 s99, v56, 16
	v_readlane_b32 s100, v56, 32
	v_readlane_b32 s101, v56, 48
	s_nop 1
	v_mov_b32_e32 v57, s98
	v_add_f32_e32 v57, s99, v57
	v_mov_b32_e32 v56, s100
	v_add_f32_e32 v56, s101, v56
	v_add_f32_e32 v56, v56, v57
	v_lshl_add_u64 v[84:85], v[78:79], 0, s[6:7]
	v_fmamk_f32 v56, v56, 0x3a800000, v68
	v_rsq_f32_e32 v80, v56
	s_waitcnt vmcnt(7)
	v_pk_add_f32 v[54:55], v[72:73], 1.0 op_sel_hi:[1,0]
	v_pk_mul_f32 v[46:47], v[46:47], v[80:81] op_sel_hi:[1,0]
	v_pk_mul_f32 v[44:45], v[44:45], v[80:81] op_sel_hi:[1,0]
	v_pk_mul_f32 v[46:47], v[2:3], v[46:47]
	v_pk_mul_f32 v[44:45], v[0:1], v[44:45]
	v_pk_add_f32 v[56:57], v[70:71], 1.0 op_sel_hi:[1,0]
	s_waitcnt vmcnt(6)
	v_pk_fma_f32 v[46:47], v[54:55], v[46:47], v[76:77]
	v_pk_fma_f32 v[44:45], v[56:57], v[44:45], v[74:75]
	v_pk_mul_f32 v[42:43], v[42:43], v[80:81] op_sel_hi:[1,0]
	v_cvt_pk_bf16_f32 v44, v44, v45
	v_cvt_pk_bf16_f32 v45, v46, v47
	global_store_dwordx2 v[82:83], v[44:45], off
	s_waitcnt vmcnt(5)
	v_mov_b32_e32 v44, v104
	v_mov_b32_e32 v45, v105
	v_mov_b32_e32 v46, v106
	v_mov_b32_e32 v47, v107
	s_nop 0
	v_mov_b32_e32 v54, v108
	v_mov_b32_e32 v55, v109
	v_mov_b32_e32 v56, v110
	v_mov_b32_e32 v57, v111
	v_pk_mul_f32 v[40:41], v[40:41], v[80:81] op_sel_hi:[1,0]
	v_pk_mul_f32 v[42:43], v[6:7], v[42:43]
	v_pk_mul_f32 v[40:41], v[4:5], v[40:41]
	v_pk_mul_f32 v[38:39], v[38:39], v[80:81] op_sel_hi:[1,0]
	v_pk_mul_f32 v[36:37], v[36:37], v[80:81] op_sel_hi:[1,0]
	v_pk_mul_f32 v[38:39], v[10:11], v[38:39]
	v_pk_mul_f32 v[36:37], v[8:9], v[36:37]
	v_pk_mul_f32 v[34:35], v[34:35], v[80:81] op_sel_hi:[1,0]
	v_pk_mul_f32 v[32:33], v[32:33], v[80:81] op_sel_hi:[1,0]
	v_pk_mul_f32 v[34:35], v[14:15], v[34:35]
	v_pk_mul_f32 v[32:33], v[12:13], v[32:33]
	s_waitcnt vmcnt(5)
	v_pk_add_f32 v[46:47], v[46:47], 1.0 op_sel_hi:[1,0]
	v_pk_add_f32 v[44:45], v[44:45], 1.0 op_sel_hi:[1,0]
	s_waitcnt vmcnt(5)
	v_pk_fma_f32 v[42:43], v[46:47], v[42:43], v[56:57]
	v_pk_fma_f32 v[40:41], v[44:45], v[40:41], v[54:55]
	v_mul_f32_e32 v54, v17, v17
	v_cvt_pk_bf16_f32 v40, v40, v41
	v_cvt_pk_bf16_f32 v41, v42, v43
	global_store_dwordx2 v[82:83], v[40:41], off offset:512
	s_waitcnt vmcnt(4)
	v_mov_b32_e32 v40, v112
	v_mov_b32_e32 v41, v113
	v_mov_b32_e32 v42, v114
	v_mov_b32_e32 v43, v115
	s_nop 0
	v_mov_b32_e32 v44, v116
	v_mov_b32_e32 v45, v117
	v_mov_b32_e32 v46, v118
	v_mov_b32_e32 v47, v119
	v_mul_f32_e32 v55, v19, v19
	v_mul_f32_e32 v56, v29, v29
	v_mul_f32_e32 v57, v31, v31
	v_fmac_f32_e32 v54, v16, v16
	v_fmac_f32_e32 v55, v18, v18
	v_fmac_f32_e32 v56, v28, v28
	v_fmac_f32_e32 v57, v30, v30
	s_waitcnt vmcnt(4)
	v_pk_add_f32 v[42:43], v[42:43], 1.0 op_sel_hi:[1,0]
	v_pk_add_f32 v[40:41], v[40:41], 1.0 op_sel_hi:[1,0]
	s_waitcnt vmcnt(4)
	v_pk_fma_f32 v[38:39], v[42:43], v[38:39], v[46:47]
	v_pk_fma_f32 v[36:37], v[40:41], v[36:37], v[44:45]
	v_mul_f32_e32 v46, v25, v25
	v_cvt_pk_bf16_f32 v36, v36, v37
	v_cvt_pk_bf16_f32 v37, v38, v39
	global_store_dwordx2 v[82:83], v[36:37], off offset:1024
	s_waitcnt vmcnt(3)
	v_mov_b32_e32 v38, v120
	v_mov_b32_e32 v39, v121
	v_mov_b32_e32 v40, v122
	v_mov_b32_e32 v41, v123
	v_mov_b32_e32 v42, v124
	v_mov_b32_e32 v43, v125
	v_mov_b32_e32 v44, v126
	v_mov_b32_e32 v45, v127
	v_mul_f32_e32 v36, v21, v21
	v_mul_f32_e32 v37, v23, v23
	v_mul_f32_e32 v47, v27, v27
	v_fmac_f32_e32 v36, v20, v20
	v_fmac_f32_e32 v37, v22, v22
	v_fmac_f32_e32 v46, v24, v24
	v_fmac_f32_e32 v47, v26, v26
	v_add_f32_e32 v36, v36, v37
	v_add_f32_e32 v37, v46, v47
	v_add_f32_e32 v46, v54, v55
	v_add_f32_e32 v36, v36, v37
	v_add_f32_e32 v47, v56, v57
	v_add_f32_e32 v36, v36, v46
	v_add_f32_e32 v36, v36, v47
	s_nop 1
	v_add_f32_dpp v36, v36, v36 quad_perm:[1,0,3,2] row_mask:0xf bank_mask:0xf bound_ctrl:1
	s_nop 1
	v_add_f32_dpp v36, v36, v36 quad_perm:[2,3,0,1] row_mask:0xf bank_mask:0xf bound_ctrl:1
	s_nop 1
	v_add_f32_dpp v36, v36, v36 row_half_mirror row_mask:0xf bank_mask:0xf bound_ctrl:1
	s_nop 1
	v_add_f32_dpp v36, v36, v36 row_mirror row_mask:0xf bank_mask:0xf bound_ctrl:1
	s_nop 1
	v_readlane_b32 s98, v36, 0
	v_readlane_b32 s99, v36, 16
	v_readlane_b32 s100, v36, 32
	v_readlane_b32 s101, v36, 48
	s_nop 1
	v_mov_b32_e32 v37, s98
	v_add_f32_e32 v37, s99, v37
	v_mov_b32_e32 v36, s100
	v_add_f32_e32 v36, s101, v36
	v_add_f32_e32 v36, v36, v37
	s_waitcnt vmcnt(3)
	v_pk_add_f32 v[40:41], v[40:41], 1.0 op_sel_hi:[1,0]
	v_pk_add_f32 v[38:39], v[38:39], 1.0 op_sel_hi:[1,0]
	s_waitcnt vmcnt(3)
	v_pk_fma_f32 v[34:35], v[34:35], v[40:41], v[44:45]
	v_pk_fma_f32 v[32:33], v[32:33], v[38:39], v[42:43]
	s_nop 0
	v_cvt_pk_bf16_f32 v32, v32, v33
	v_cvt_pk_bf16_f32 v33, v34, v35
	global_store_dwordx2 v[82:83], v[32:33], off offset:1536
	s_and_saveexec_b64 s[0:1], vcc
	s_cbranch_execz .LBB0_140
	v_min_i32_e32 v32, 0x10000, v52
	v_ashrrev_i32_e32 v32, 13, v32
	v_mul_i32_i24_e32 v32, 0x1800, v32
	v_ashrrev_i32_e32 v33, 31, v32
	v_lshl_add_u64 v[32:33], v[32:33], 2, s[24:25]
	v_lshl_add_u64 v[42:43], v[32:33], 0, v[48:49]
	v_add_co_u32_e32 v32, vcc, s10, v42
	s_waitcnt lgkmcnt(0)
	v_addc_co_u32_e32 v33, vcc, 0, v43, vcc
	global_load_dwordx4 v[32:35], v[32:33], off
	s_nop 0
	global_load_dwordx4 v[38:41], v[42:43], off
	v_lshl_add_u64 v[102:103], v[42:43], 0, s[6:7]
	global_load_dwordx4 v[128:131], v[102:103], off offset:1024
	global_load_dwordx4 v[132:135], v[42:43], off offset:1024
	global_load_dwordx4 v[136:139], v[102:103], off offset:2048
	global_load_dwordx4 v[140:143], v[42:43], off offset:2048
	global_load_dwordx4 v[144:147], v[102:103], off offset:3072
	global_load_dwordx4 v[148:151], v[42:43], off offset:3072
	v_fmamk_f32 v36, v36, 0x3a800000, v68
	v_rsq_f32_e32 v36, v36
	v_lshlrev_b64 v[44:45], 11, v[52:53]
	v_lshl_add_u64 v[44:45], v[50:51], 0, v[44:45]
	v_lshl_add_u64 v[46:47], v[42:43], 0, s[6:7]
	v_pk_mul_f32 v[22:23], v[22:23], v[36:37] op_sel_hi:[1,0]
	v_pk_mul_f32 v[20:21], v[20:21], v[36:37] op_sel_hi:[1,0]
	v_pk_mul_f32 v[22:23], v[2:3], v[22:23]
	v_pk_mul_f32 v[20:21], v[0:1], v[20:21]
	v_pk_mul_f32 v[26:27], v[26:27], v[36:37] op_sel_hi:[1,0]
	v_pk_mul_f32 v[24:25], v[24:25], v[36:37] op_sel_hi:[1,0]
	v_pk_mul_f32 v[26:27], v[6:7], v[26:27]
	v_pk_mul_f32 v[24:25], v[4:5], v[24:25]
	v_pk_mul_f32 v[18:19], v[18:19], v[36:37] op_sel_hi:[1,0]
	v_pk_mul_f32 v[16:17], v[16:17], v[36:37] op_sel_hi:[1,0]
	v_pk_mul_f32 v[18:19], v[10:11], v[18:19]
	v_pk_mul_f32 v[16:17], v[8:9], v[16:17]
	s_waitcnt vmcnt(7)
	v_pk_add_f32 v[34:35], v[34:35], 1.0 op_sel_hi:[1,0]
	v_pk_add_f32 v[32:33], v[32:33], 1.0 op_sel_hi:[1,0]
	s_waitcnt vmcnt(6)
	v_pk_fma_f32 v[22:23], v[22:23], v[34:35], v[40:41]
	v_pk_fma_f32 v[20:21], v[20:21], v[32:33], v[38:39]
	s_nop 0
	v_cvt_pk_bf16_f32 v20, v20, v21
	v_cvt_pk_bf16_f32 v21, v22, v23
	global_store_dwordx2 v[44:45], v[20:21], off
	s_waitcnt vmcnt(5)
	v_mov_b32_e32 v20, v128
	v_mov_b32_e32 v21, v129
	v_mov_b32_e32 v22, v130
	v_mov_b32_e32 v23, v131
	s_nop 0
	v_mov_b32_e32 v32, v132
	v_mov_b32_e32 v33, v133
	v_mov_b32_e32 v34, v134
	v_mov_b32_e32 v35, v135
	s_waitcnt vmcnt(5)
	v_pk_add_f32 v[22:23], v[22:23], 1.0 op_sel_hi:[1,0]
	v_pk_add_f32 v[20:21], v[20:21], 1.0 op_sel_hi:[1,0]
	s_waitcnt vmcnt(5)
	v_pk_fma_f32 v[22:23], v[26:27], v[22:23], v[34:35]
	v_pk_fma_f32 v[20:21], v[24:25], v[20:21], v[32:33]
	s_nop 0
	v_cvt_pk_bf16_f32 v20, v20, v21
	v_cvt_pk_bf16_f32 v21, v22, v23
	global_store_dwordx2 v[44:45], v[20:21], off offset:512
	s_waitcnt vmcnt(4)
	v_mov_b32_e32 v20, v136
	v_mov_b32_e32 v21, v137
	v_mov_b32_e32 v22, v138
	v_mov_b32_e32 v23, v139
	s_nop 0
	v_mov_b32_e32 v24, v140
	v_mov_b32_e32 v25, v141
	v_mov_b32_e32 v26, v142
	v_mov_b32_e32 v27, v143
	s_waitcnt vmcnt(4)
	v_pk_add_f32 v[22:23], v[22:23], 1.0 op_sel_hi:[1,0]
	v_pk_add_f32 v[20:21], v[20:21], 1.0 op_sel_hi:[1,0]
	s_waitcnt vmcnt(4)
	v_pk_fma_f32 v[18:19], v[18:19], v[22:23], v[26:27]
	v_pk_fma_f32 v[16:17], v[16:17], v[20:21], v[24:25]
	v_pk_mul_f32 v[24:25], v[30:31], v[36:37] op_sel_hi:[1,0]
	v_cvt_pk_bf16_f32 v16, v16, v17
	v_cvt_pk_bf16_f32 v17, v18, v19
	global_store_dwordx2 v[44:45], v[16:17], off offset:1024
	s_waitcnt vmcnt(3)
	v_mov_b32_e32 v16, v144
	v_mov_b32_e32 v17, v145
	v_mov_b32_e32 v18, v146
	v_mov_b32_e32 v19, v147
	s_nop 0
	v_mov_b32_e32 v20, v148
	v_mov_b32_e32 v21, v149
	v_mov_b32_e32 v22, v150
	v_mov_b32_e32 v23, v151
	v_pk_mul_f32 v[26:27], v[28:29], v[36:37] op_sel_hi:[1,0]
	v_pk_mul_f32 v[24:25], v[14:15], v[24:25]
	v_pk_mul_f32 v[26:27], v[12:13], v[26:27]
	s_waitcnt vmcnt(3)
	v_pk_add_f32 v[18:19], v[18:19], 1.0 op_sel_hi:[1,0]
	v_pk_add_f32 v[16:17], v[16:17], 1.0 op_sel_hi:[1,0]
	s_waitcnt vmcnt(3)
	v_pk_fma_f32 v[18:19], v[24:25], v[18:19], v[22:23]
	v_pk_fma_f32 v[16:17], v[26:27], v[16:17], v[20:21]
	s_nop 0
	v_cvt_pk_bf16_f32 v16, v16, v17
	v_cvt_pk_bf16_f32 v17, v18, v19
	global_store_dwordx2 v[44:45], v[16:17], off offset:1536
	s_branch .LBB0_140
